# grid barrier: local arrivers number 0 and 16 of each XCD start an early L2 writeback (leader still writes back after the last arrival)
# baseline (speedup 1.0000x reference)
; __device__ __forceinline__ unsigned xb_add(unsigned* p, unsigned v) { return __hip_atomic_fetch_add(p, v, __ATOMIC_RELAXED, __HIP_MEMORY_SCOPE_AGENT); }
; __device__ __forceinline__ void xcd_barrier(const XcdBarrier& b) {
;     ...
;         const unsigned old = xb_add(&bar[XB_XSUB(b.x)], 1u);
;         const unsigned gen = old / nloc;
;         if (old + 1u == (gen + 1u) * nloc) {
.LBB0_1148:
	s_or_b64 exec, exec, s[2:3]
	v_cvt_f32_u32_e32 v4, v2
	s_waitcnt vmcnt(0)
	v_readfirstlane_b32 s2, v3
	v_sub_u32_e32 v3, 0, v2
	v_rcp_iflag_f32_e32 v4, v4
	v_add_u32_e32 v5, s2, v1
	v_mul_f32_e32 v4, 0x4f7ffffe, v4
	v_cvt_u32_f32_e32 v4, v4
	v_mul_lo_u32 v1, v3, v4
	v_mul_hi_u32 v1, v4, v1
	v_add_u32_e32 v1, v4, v1
	v_mul_hi_u32 v1, v5, v1
	v_mul_lo_u32 v3, v1, v2
	v_sub_u32_e32 v3, v5, v3
	v_add_u32_e32 v4, 1, v1
	v_cmp_ge_u32_e32 vcc, v3, v2
	s_nop 1
	v_cndmask_b32_e32 v1, v1, v4, vcc
	v_sub_u32_e32 v4, v3, v2
	v_cndmask_b32_e32 v3, v3, v4, vcc
	v_add_u32_e32 v4, 1, v1
	v_cmp_ge_u32_e32 vcc, v3, v2
	v_add_u32_e32 v3, 1, v5
	s_nop 0
	v_cndmask_b32_e32 v1, v1, v4, vcc
	v_mul_lo_u32 v4, v2, v1
	v_add_u32_e32 v2, v4, v2
	v_cmp_ne_u32_e32 vcc, v3, v2
	s_and_saveexec_b64 s[2:3], vcc
	s_xor_b64 s[18:19], exec, s[2:3]
	s_cbranch_execz .LBB0_1162
	v_sub_u32_e32 v3, v5, v4
	v_and_b32_e32 v3, 15, v3
	v_cmp_eq_u32_e32 vcc, 0, v3
	s_cbranch_vccz .Lxb_noflush
	buffer_wbl2 sc1
.Lxb_noflush:
	v_readlane_b32 s2, v254, 42

; __device__ __forceinline__ unsigned xb_ld(unsigned* p)              { return __hip_atomic_load(p, __ATOMIC_RELAXED, __HIP_MEMORY_SCOPE_AGENT); }
; #define XB_SPIN(cond, bar) do { unsigned _sp = 0; while (cond) { __builtin_amdgcn_s_sleep(1); \
;     if ((++_sp & 255u) == 0u) { if (xb_ld(&(bar)[XB_TMO])) break; if (_sp > XB_SPIN_CAP) { atomicAdd(&(bar)[XB_TMO], 1u); break; } } } } while (0)
; __device__ __forceinline__ void xcd_barrier(const XcdBarrier& b) {
;     ...
;         } else {
;             XB_SPIN(xb_ld(&bar[XB_XGEN(b.x)]) == gen, bar);
;             __builtin_amdgcn_fence(__ATOMIC_ACQUIRE, "agent");
	v_readlane_b32 s3, v254, 43
	s_waitcnt lgkmcnt(0)
	s_nop 3
	global_load_dword v0, v181, s[2:3] sc1
	s_waitcnt vmcnt(0)
	v_cmp_eq_u32_e32 vcc, v0, v1
	s_and_saveexec_b64 s[38:39], vcc
	s_cbranch_execz .LBB0_1161
	s_mov_b32 s4, 1
	s_mov_b64 s[40:41], 0
	s_branch .LBB0_1152
